# A/B of the static attention-phase priority raise: waves 0-3 instead of waves 4-7
# speedup vs baseline: 1.0034x; 1.0034x over previous
.LBB0_742:
	s_or_b64 exec, exec, s[2:3]
	s_mov_b64 s[0:1], s[66:67]
	s_waitcnt lgkmcnt(0)
	s_barrier
	v_readfirstlane_b32 s100, v180
	s_nop 1
	s_bfe_u32 s100, s100, 0x10008
	s_cmp_lg_u32 s100, 0
	s_cbranch_scc1 .Lattn_noprio
	s_setprio 1
